# attention tiles: softmax row sums via v_pk_add_f32 (16 instead of 31 adds per tile; summation order changes, same f32 precision; baseline source also uses packed f32 adds here)
# baseline (speedup 1.0000x reference)
; DI void attn_tile(LAS const unsigned char* Ks, LAS const unsigned char* VT, const bf16x8 (&qf)[4], int ql, int hi,
;                   bool need_mask, bool col_en, int lo_b, int hi_b, float& m_ref, float& l_run, f32x16 (&o)[2], f32x16 (&sp)[2]) {
;     ...
;     const float bias = col_en ? -m_ref : -INFINITY;
;     const bool plain = __all(col_en && (m_ref == 0.f));
; #pragma unroll
;     for (int p = 0; p < 2; ++p) {
;         bf16x8 kf[4];
; #pragma unroll
;         for (int d0 = 0; d0 < 4; ++d0) { const int c = 2 * d0 + hi; kf[d0] = *(LAS const bf16x8*)(Ks + c * 1024 + ((ql + 32 * p) << 4)); }
;         f32x16 acc;
;         if (plain) {
; #pragma unroll
;             for (int r = 0; r < 16; ++r) acc[r] = 0.f;
; #pragma unroll
;             for (int d0 = 0; d0 < 4; ++d0) acc = MFMA32(kf[d0], qf[d0], acc);
;         } else {
; #pragma unroll
;             for (int r = 0; r < 16; ++r) acc[r] = bias;
; #pragma unroll
;             for (int d0 = 0; d0 < 4; ++d0) acc = MFMA32(kf[d0], qf[d0], acc);
;         }
;         sp[p] = acc;
;     }
;     if (need_mask) {
; #pragma unroll
;         for (int p = 0; p < 2; ++p)
; #pragma unroll
;             for (int r = 0; r < 16; ++r) { const int kvl = 32 * p + (r & 3) + 8 * (r >> 2) + 4 * hi; const bool ok = (kvl <= hi_b) && (kvl > lo_b); sp[p][r] = ok ? sp[p][r] : -INFINITY; }
;     }
;     float tm = fmaxf(fmaxf(sp[0][0], sp[0][1]), sp[1][0]);
; #pragma unroll
;     for (int r = 2; r < 16; r += 2) tm = fmaxf(fmaxf(tm, sp[0][r]), sp[0][r + 1]);
; #pragma unroll
;     for (int r = 1; r < 15; r += 2) tm = fmaxf(fmaxf(tm, sp[1][r]), sp[1][r + 1]);
;     tm = fmaxf(tm, sp[1][15]);
;     tm = half_max(tm);
;     if (__any((tm > 16.f) || ((tm < -16.f) && (tm > -INFINITY)))) {
;         const bool up = tm > 16.f;
;         const bool dn = (tm < -16.f) && (tm > -INFINITY) && (half_sum(l_run) == 0.f);
;         const float dlt = (up || dn) ? tm : 0.f;
;         const float alpha = up ? fast_exp2(-dlt) : 1.0f;
;         l_run *= alpha; m_ref += dlt;
; #pragma unroll
;         for (int r = 0; r < 16; ++r) { o[0][r] *= alpha; o[1][r] *= alpha; sp[0][r] -= dlt; sp[1][r] -= dlt; }
;     }
;     f32x2_t ps = {0.f, 0.f};
; #pragma unroll
;     for (int r = 0; r < 16; ++r) { const float e0 = fast_exp2(sp[0][r]), e1 = fast_exp2(sp[1][r]); sp[0][r] = e0; sp[1][r] = e1; ps += (f32x2_t){e0, e1}; }
;     l_run += ps[0] + ps[1];
.Lat_hot_S:
	s_waitcnt vmcnt(2) lgkmcnt(0)
	s_barrier
	ds_read_b128 v[84:87], v134
	ds_read_b128 v[88:91], v134 offset:2048
	ds_read_b128 v[92:95], v134 offset:4096
	ds_read_b128 v[96:99], v134 offset:6144
	ds_read_b128 v[100:103], v134 offset:512
	ds_read_b128 v[104:107], v134 offset:2560
	ds_read_b128 v[108:111], v134 offset:4608
	ds_read_b128 v[112:115], v134 offset:6656
	ds_read_b32 v140, v136 offset:4
	ds_read_b32 v142, v136 offset:12
	v_pk_add_f32 v[118:119], v[50:51], v[52:53]
	v_cvt_pk_bf16_f32 v224, v50, v51
	v_pk_add_f32 v[122:123], v[54:55], v[56:57]
	v_cvt_pk_bf16_f32 v225, v52, v53
	v_pk_add_f32 v[124:125], v[34:35], v[36:37]
	v_cvt_pk_bf16_f32 v226, v54, v55
	v_pk_add_f32 v[118:119], v[118:119], v[58:59]
	v_cvt_pk_bf16_f32 v227, v56, v57
	v_pk_add_f32 v[122:123], v[122:123], v[60:61]
	v_cvt_pk_bf16_f32 v228, v58, v59
	v_pk_add_f32 v[124:125], v[124:125], v[38:39]
	v_cvt_pk_bf16_f32 v229, v60, v61
	v_pk_add_f32 v[118:119], v[118:119], v[62:63]
	v_cvt_pk_bf16_f32 v230, v62, v63
	v_pk_add_f32 v[122:123], v[122:123], v[64:65]
	v_cvt_pk_bf16_f32 v231, v64, v65
	v_pk_add_f32 v[124:125], v[124:125], v[40:41]
	v_cvt_pk_bf16_f32 v232, v34, v35
	v_pk_add_f32 v[118:119], v[118:119], v[42:43]
	v_cvt_pk_bf16_f32 v233, v36, v37
	v_pk_add_f32 v[122:123], v[122:123], v[44:45]
	v_cvt_pk_bf16_f32 v234, v38, v39
	v_pk_add_f32 v[124:125], v[124:125], v[46:47]
	v_cvt_pk_bf16_f32 v235, v40, v41
	v_pk_add_f32 v[118:119], v[118:119], v[48:49]
	v_cvt_pk_bf16_f32 v236, v42, v43
	v_pk_add_f32 v[118:119], v[118:119], v[122:123]
	v_cvt_pk_bf16_f32 v237, v44, v45
	v_pk_add_f32 v[118:119], v[118:119], v[124:125]
	v_cvt_pk_bf16_f32 v238, v46, v47
	v_add_f32_e32 v118, v118, v119
	v_cvt_pk_bf16_f32 v239, v48, v49
	s_cmp_eq_u32 s69, 1
	s_cbranch_scc1 .Lat_hcep_19
	v_cndmask_b32_e64 v118, 0, v118, s[16:17]
	v_cndmask_b32_e64 v224, 0, v224, s[16:17]
	v_cndmask_b32_e64 v225, 0, v225, s[16:17]
	v_cndmask_b32_e64 v226, 0, v226, s[16:17]
	v_cndmask_b32_e64 v227, 0, v227, s[16:17]
	v_cndmask_b32_e64 v228, 0, v228, s[16:17]
	v_cndmask_b32_e64 v229, 0, v229, s[16:17]
	v_cndmask_b32_e64 v230, 0, v230, s[16:17]
	v_cndmask_b32_e64 v231, 0, v231, s[16:17]
	v_cndmask_b32_e64 v232, 0, v232, s[16:17]
	v_cndmask_b32_e64 v233, 0, v233, s[16:17]
	v_cndmask_b32_e64 v234, 0, v234, s[16:17]
	v_cndmask_b32_e64 v235, 0, v235, s[16:17]
	v_cndmask_b32_e64 v236, 0, v236, s[16:17]
	v_cndmask_b32_e64 v237, 0, v237, s[16:17]
	v_cndmask_b32_e64 v238, 0, v238, s[16:17]
	v_cndmask_b32_e64 v239, 0, v239, s[16:17]

; #define LAS __attribute__((address_space(3)))
; DI void attn_tile(LAS const unsigned char* Ks, LAS const unsigned char* VT, const bf16x8 (&qf)[4], int ql, int hi,
;                   bool need_mask, bool col_en, int lo_b, int hi_b, float& m_ref, float& l_run, f32x16 (&o)[2], f32x16 (&sp)[2]) {
;     ...
;         bf16x8 kf[4];
; #pragma unroll
;         for (int d0 = 0; d0 < 4; ++d0) { const int c = 2 * d0 + hi; kf[d0] = *(LAS const bf16x8*)(Ks + c * 1024 + ((ql + 32 * p) << 4)); }
;         f32x16 acc;
;         if (plain) {
; #pragma unroll
;             for (int r = 0; r < 16; ++r) acc[r] = 0.f;
; #pragma unroll
;             for (int d0 = 0; d0 < 4; ++d0) acc = MFMA32(kf[d0], qf[d0], acc);
;         } else {
; #pragma unroll
;             for (int r = 0; r < 16; ++r) acc[r] = bias;
; #pragma unroll
;             for (int d0 = 0; d0 < 4; ++d0) acc = MFMA32(kf[d0], qf[d0], acc);
;         }
;         sp[p] = acc;
;     }
;     if (need_mask) {
; #pragma unroll
;         for (int p = 0; p < 2; ++p)
; #pragma unroll
;             for (int r = 0; r < 16; ++r) { const int kvl = 32 * p + (r & 3) + 8 * (r >> 2) + 4 * hi; const bool ok = (kvl <= hi_b) && (kvl > lo_b); sp[p][r] = ok ? sp[p][r] : -INFINITY; }
;     }
;     float tm = fmaxf(fmaxf(sp[0][0], sp[0][1]), sp[1][0]);
; #pragma unroll
;     for (int r = 2; r < 16; r += 2) tm = fmaxf(fmaxf(tm, sp[0][r]), sp[0][r + 1]);
; #pragma unroll
;     for (int r = 1; r < 15; r += 2) tm = fmaxf(fmaxf(tm, sp[1][r]), sp[1][r + 1]);
;     tm = fmaxf(tm, sp[1][15]);
;     tm = half_max(tm);
;     if (__any((tm > 16.f) || ((tm < -16.f) && (tm > -INFINITY)))) {
;         const bool up = tm > 16.f;
;         const bool dn = (tm < -16.f) && (tm > -INFINITY) && (half_sum(l_run) == 0.f);
;         const float dlt = (up || dn) ? tm : 0.f;
;         const float alpha = up ? fast_exp2(-dlt) : 1.0f;
;         l_run *= alpha; m_ref += dlt;
; #pragma unroll
;         for (int r = 0; r < 16; ++r) { o[0][r] *= alpha; o[1][r] *= alpha; sp[0][r] -= dlt; sp[1][r] -= dlt; }
;     }
;     f32x2_t ps = {0.f, 0.f};
; #pragma unroll
;     for (int r = 0; r < 16; ++r) { const float e0 = fast_exp2(sp[0][r]), e1 = fast_exp2(sp[1][r]); sp[0][r] = e0; sp[1][r] = e1; ps += (f32x2_t){e0, e1}; }
;     l_run += ps[0] + ps[1];
;     bf16x8 pk[2][2];
; #pragma unroll
;     for (int p = 0; p < 2; ++p)
; #pragma unroll
.Lat_hot_W:
	s_waitcnt vmcnt(2) lgkmcnt(0)
	s_barrier
	ds_read_b128 v[84:87], v134
	ds_read_b128 v[88:91], v134 offset:2048
	ds_read_b128 v[92:95], v134 offset:4096
	ds_read_b128 v[96:99], v134 offset:6144
	ds_read_b128 v[100:103], v134 offset:512
	ds_read_b128 v[104:107], v134 offset:2560
	ds_read_b128 v[108:111], v134 offset:4608
	ds_read_b128 v[112:115], v134 offset:6656
	v_pk_add_f32 v[118:119], v[50:51], v[52:53]
	v_cvt_pk_bf16_f32 v224, v50, v51
	v_pk_add_f32 v[122:123], v[54:55], v[56:57]
	v_cvt_pk_bf16_f32 v225, v52, v53
	v_pk_add_f32 v[124:125], v[34:35], v[36:37]
	v_cvt_pk_bf16_f32 v226, v54, v55
	v_pk_add_f32 v[118:119], v[118:119], v[58:59]
	v_cvt_pk_bf16_f32 v227, v56, v57
	v_pk_add_f32 v[122:123], v[122:123], v[60:61]
	v_cvt_pk_bf16_f32 v228, v58, v59
	v_pk_add_f32 v[124:125], v[124:125], v[38:39]
	v_cvt_pk_bf16_f32 v229, v60, v61
	v_pk_add_f32 v[118:119], v[118:119], v[62:63]
	v_cvt_pk_bf16_f32 v230, v62, v63
	v_pk_add_f32 v[122:123], v[122:123], v[64:65]
	v_cvt_pk_bf16_f32 v231, v64, v65
	v_pk_add_f32 v[124:125], v[124:125], v[40:41]
	v_cvt_pk_bf16_f32 v232, v34, v35
	v_pk_add_f32 v[118:119], v[118:119], v[42:43]
	v_cvt_pk_bf16_f32 v233, v36, v37
	v_pk_add_f32 v[122:123], v[122:123], v[44:45]
	v_cvt_pk_bf16_f32 v234, v38, v39
	v_pk_add_f32 v[124:125], v[124:125], v[46:47]
	v_cvt_pk_bf16_f32 v235, v40, v41
	v_pk_add_f32 v[118:119], v[118:119], v[48:49]
	v_cvt_pk_bf16_f32 v236, v42, v43
	v_pk_add_f32 v[118:119], v[118:119], v[122:123]
	v_cvt_pk_bf16_f32 v237, v44, v45
	v_pk_add_f32 v[118:119], v[118:119], v[124:125]
	v_cvt_pk_bf16_f32 v238, v46, v47
	v_add_f32_e32 v118, v118, v119
	v_cvt_pk_bf16_f32 v239, v48, v49
	v_add_f32_e32 v141, v141, v118
	s_mov_b32 m0, s63
	v_lshl_add_u64 v[190:191], v[190:191], 0, s[46:47]
	v_lshl_add_u64 v[82:83], v[82:83], 0, s[46:47]
	global_load_lds_dwordx4 v[190:191], off
	s_add_i32 m0, s63, 0x2000
	s_nop 0
	global_load_lds_dwordx4 v[82:83], off
	s_waitcnt lgkmcnt(0)
	v_mfma_f32_32x32x16_bf16 v[50:65], v[84:87], v[66:69], 0
	ds_read_b64_tr_b16 v[192:193], v135 offset:8192
	ds_read_b64_tr_b16 v[194:195], v135 offset:8704
	v_mfma_f32_32x32x16_bf16 v[50:65], v[88:91], v[70:73], v[50:65]
	ds_read_b64_tr_b16 v[208:209], v135 offset:12288
	ds_read_b64_tr_b16 v[210:211], v135 offset:12800
	v_mfma_f32_32x32x16_bf16 v[50:65], v[92:95], v[74:77], v[50:65]
	ds_read_b64_tr_b16 v[196:197], v135 offset:9216
	ds_read_b64_tr_b16 v[198:199], v135 offset:9728
	v_mfma_f32_32x32x16_bf16 v[50:65], v[96:99], v[78:81], v[50:65]
	ds_read_b64_tr_b16 v[212:213], v135 offset:13312
	ds_read_b64_tr_b16 v[214:215], v135 offset:13824
	v_mfma_f32_32x32x16_bf16 v[34:49], v[100:103], v[66:69], 0
	ds_read_b64_tr_b16 v[200:201], v135 offset:10240
	ds_read_b64_tr_b16 v[202:203], v135 offset:10752
	v_mfma_f32_32x32x16_bf16 v[34:49], v[104:107], v[70:73], v[34:49]
	ds_read_b64_tr_b16 v[216:217], v135 offset:14336
	ds_read_b64_tr_b16 v[218:219], v135 offset:14848
	v_mfma_f32_32x32x16_bf16 v[34:49], v[108:111], v[74:77], v[34:49]
	ds_read_b64_tr_b16 v[204:205], v135 offset:11264
	ds_read_b64_tr_b16 v[206:207], v135 offset:11776
	v_mfma_f32_32x32x16_bf16 v[34:49], v[112:115], v[78:81], v[34:49]
	ds_read_b64_tr_b16 v[220:221], v135 offset:15360
	ds_read_b64_tr_b16 v[222:223], v135 offset:15872
	s_waitcnt lgkmcnt(8)
	v_mfma_f32_32x32x16_bf16 v[18:33], v[192:195], v[224:227], v[18:33]
	v_mfma_f32_32x32x16_bf16 v[2:17], v[208:211], v[224:227], v[2:17]
	v_mfma_f32_32x32x16_bf16 v[18:33], v[196:199], v[228:231], v[18:33]
	v_mfma_f32_32x32x16_bf16 v[2:17], v[212:215], v[228:231], v[2:17]
	v_max3_f32 v245, v50, v51, v52
	v_max3_f32 v245, v245, v53, v54
	v_max3_f32 v245, v245, v55, v56
	v_max3_f32 v245, v245, v57, v58
	v_max3_f32 v245, v245, v59, v60
	v_max3_f32 v245, v245, v61, v62
	v_max3_f32 v245, v245, v63, v64
	v_max3_f32 v245, v245, v65, v34
	v_max3_f32 v245, v245, v35, v36
	v_max3_f32 v245, v245, v37, v38
	v_max3_f32 v245, v245, v39, v40
	v_max3_f32 v245, v245, v41, v42
	v_max3_f32 v245, v245, v43, v44
	v_max3_f32 v245, v245, v45, v46
	v_max3_f32 v245, v245, v47, v48
	v_max_f32_e32 v245, v245, v49
	v_mov_b32_e32 v246, v245
	s_nop 1
	v_permlane32_swap_b32_e32 v245, v246
	v_max_f32_e32 v245, v245, v246
	v_cmp_gt_f32_e64 vcc, |v245|, s65
	s_cmp_lg_u64 vcc, 0
	s_cbranch_scc1 .Lat_rare_W

; #define LAS __attribute__((address_space(3)))
; DI void attn_tile(LAS const unsigned char* Ks, LAS const unsigned char* VT, const bf16x8 (&qf)[4], int ql, int hi,
;                   bool need_mask, bool col_en, int lo_b, int hi_b, float& m_ref, float& l_run, f32x16 (&o)[2], f32x16 (&sp)[2]) {
;     ...
;         bf16x8 kf[4];
; #pragma unroll
;         for (int d0 = 0; d0 < 4; ++d0) { const int c = 2 * d0 + hi; kf[d0] = *(LAS const bf16x8*)(Ks + c * 1024 + ((ql + 32 * p) << 4)); }
;         f32x16 acc;
;         if (plain) {
; #pragma unroll
;             for (int r = 0; r < 16; ++r) acc[r] = 0.f;
; #pragma unroll
;             for (int d0 = 0; d0 < 4; ++d0) acc = MFMA32(kf[d0], qf[d0], acc);
;         } else {
; #pragma unroll
;             for (int r = 0; r < 16; ++r) acc[r] = bias;
; #pragma unroll
;             for (int d0 = 0; d0 < 4; ++d0) acc = MFMA32(kf[d0], qf[d0], acc);
;         }
;         sp[p] = acc;
;     }
;     if (need_mask) {
; #pragma unroll
;         for (int p = 0; p < 2; ++p)
; #pragma unroll
;             for (int r = 0; r < 16; ++r) { const int kvl = 32 * p + (r & 3) + 8 * (r >> 2) + 4 * hi; const bool ok = (kvl <= hi_b) && (kvl > lo_b); sp[p][r] = ok ? sp[p][r] : -INFINITY; }
;     }
;     float tm = fmaxf(fmaxf(sp[0][0], sp[0][1]), sp[1][0]);
; #pragma unroll
;     for (int r = 2; r < 16; r += 2) tm = fmaxf(fmaxf(tm, sp[0][r]), sp[0][r + 1]);
; #pragma unroll
;     for (int r = 1; r < 15; r += 2) tm = fmaxf(fmaxf(tm, sp[1][r]), sp[1][r + 1]);
;     tm = fmaxf(tm, sp[1][15]);
;     tm = half_max(tm);
;     if (__any((tm > 16.f) || ((tm < -16.f) && (tm > -INFINITY)))) {
;         const bool up = tm > 16.f;
;         const bool dn = (tm < -16.f) && (tm > -INFINITY) && (half_sum(l_run) == 0.f);
;         const float dlt = (up || dn) ? tm : 0.f;
;         const float alpha = up ? fast_exp2(-dlt) : 1.0f;
;         l_run *= alpha; m_ref += dlt;
; #pragma unroll
;         for (int r = 0; r < 16; ++r) { o[0][r] *= alpha; o[1][r] *= alpha; sp[0][r] -= dlt; sp[1][r] -= dlt; }
;     }
;     f32x2_t ps = {0.f, 0.f};
; #pragma unroll
;     for (int r = 0; r < 16; ++r) { const float e0 = fast_exp2(sp[0][r]), e1 = fast_exp2(sp[1][r]); sp[0][r] = e0; sp[1][r] = e1; ps += (f32x2_t){e0, e1}; }
;     l_run += ps[0] + ps[1];
;     bf16x8 pk[2][2];
; #pragma unroll
;     for (int p = 0; p < 2; ++p)
; #pragma unroll
.Lat_nodma_23:
	v_add_u32_e32 v246, s79, v240
	v_mov_b32_e32 v116, s78
	ds_read_b128 v[84:87], v246
	ds_read_b128 v[88:91], v246 offset:2048
	ds_read_b128 v[92:95], v246 offset:4096
	ds_read_b128 v[96:99], v246 offset:6144
	ds_read_b128 v[100:103], v246 offset:512
	ds_read_b128 v[104:107], v246 offset:2560
	ds_read_b128 v[108:111], v246 offset:4608
	ds_read_b128 v[112:115], v246 offset:6656
	ds_read2_b32 v[254:255], v116 offset0:1 offset1:3
	s_add_i32 s9, s77, 1
	s_and_b32 s9, s9, 3
	s_lshl_b32 s9, s9, 14
	v_add_u32_e32 v126, s9, v241
	v_pk_add_f32 v[118:119], v[50:51], v[52:53]
	v_cvt_pk_bf16_f32 v224, v50, v51
	v_pk_add_f32 v[122:123], v[54:55], v[56:57]
	v_cvt_pk_bf16_f32 v225, v52, v53
	v_pk_add_f32 v[124:125], v[34:35], v[36:37]
	v_cvt_pk_bf16_f32 v226, v54, v55
	v_pk_add_f32 v[118:119], v[118:119], v[58:59]
	v_cvt_pk_bf16_f32 v227, v56, v57
	v_pk_add_f32 v[122:123], v[122:123], v[60:61]
	v_cvt_pk_bf16_f32 v228, v58, v59
	v_pk_add_f32 v[124:125], v[124:125], v[38:39]
	v_cvt_pk_bf16_f32 v229, v60, v61
	v_pk_add_f32 v[118:119], v[118:119], v[62:63]
	v_cvt_pk_bf16_f32 v230, v62, v63
	v_pk_add_f32 v[122:123], v[122:123], v[64:65]
	v_cvt_pk_bf16_f32 v231, v64, v65
	v_pk_add_f32 v[124:125], v[124:125], v[40:41]
	v_cvt_pk_bf16_f32 v232, v34, v35
	v_pk_add_f32 v[118:119], v[118:119], v[42:43]
	v_cvt_pk_bf16_f32 v233, v36, v37
	v_pk_add_f32 v[122:123], v[122:123], v[44:45]
	v_cvt_pk_bf16_f32 v234, v38, v39
	v_pk_add_f32 v[124:125], v[124:125], v[46:47]
	v_cvt_pk_bf16_f32 v235, v40, v41
	v_pk_add_f32 v[118:119], v[118:119], v[48:49]
	v_cvt_pk_bf16_f32 v236, v42, v43
	v_pk_add_f32 v[118:119], v[118:119], v[122:123]
	v_cvt_pk_bf16_f32 v237, v44, v45
	v_pk_add_f32 v[118:119], v[118:119], v[124:125]
	v_cvt_pk_bf16_f32 v238, v46, v47
	v_add_f32_e32 v118, v118, v119
	v_cvt_pk_bf16_f32 v239, v48, v49
	s_cmp_eq_u32 s21, 1
	s_cbranch_scc1 .Lat_cep_24
	v_cndmask_b32_e64 v118, 0, v118, s[16:17]
	v_cndmask_b32_e64 v224, 0, v224, s[16:17]
	v_cndmask_b32_e64 v225, 0, v225, s[16:17]
	v_cndmask_b32_e64 v226, 0, v226, s[16:17]
	v_cndmask_b32_e64 v227, 0, v227, s[16:17]
	v_cndmask_b32_e64 v228, 0, v228, s[16:17]
	v_cndmask_b32_e64 v229, 0, v229, s[16:17]
	v_cndmask_b32_e64 v230, 0, v230, s[16:17]
	v_cndmask_b32_e64 v231, 0, v231, s[16:17]
	v_cndmask_b32_e64 v232, 0, v232, s[16:17]
	v_cndmask_b32_e64 v233, 0, v233, s[16:17]
	v_cndmask_b32_e64 v234, 0, v234, s[16:17]
	v_cndmask_b32_e64 v235, 0, v235, s[16:17]
	v_cndmask_b32_e64 v236, 0, v236, s[16:17]
	v_cndmask_b32_e64 v237, 0, v237, s[16:17]
	v_cndmask_b32_e64 v238, 0, v238, s[16:17]
	v_cndmask_b32_e64 v239, 0, v239, s[16:17]

; #define LAS __attribute__((address_space(3)))
; DI unsigned pk2(float lo, float hi) { f32x2_t v = {lo, hi}; bf16x2_t b = __builtin_convertvector(v, bf16x2_t); return __builtin_bit_cast(unsigned, b); }
; DI float fast_exp2(float x) { return __builtin_amdgcn_exp2f(x); }
; DI void attn_tile(LAS const unsigned char* Ks, LAS const unsigned char* VT, const bf16x8 (&qf)[4], int ql, int hi,
;                   bool need_mask, bool col_en, int lo_b, int hi_b, float& m_ref, float& l_run, f32x16 (&o)[2], f32x16 (&sp)[2]) {
;     ...
;     f32x2_t ps = {0.f, 0.f};
; #pragma unroll
;     for (int r = 0; r < 16; ++r) { const float e0 = fast_exp2(sp[0][r]), e1 = fast_exp2(sp[1][r]); sp[0][r] = e0; sp[1][r] = e1; ps += (f32x2_t){e0, e1}; }
;     l_run += ps[0] + ps[1];
;     bf16x8 pk[2][2];
; #pragma unroll
;     for (int p = 0; p < 2; ++p)
; #pragma unroll
;         for (int s = 0; s < 2; ++s) { u32x4 w; w.x = pk2(sp[p][8 * s], sp[p][8 * s + 1]); w.y = pk2(sp[p][8 * s + 2], sp[p][8 * s + 3]); w.z = pk2(sp[p][8 * s + 4], sp[p][8 * s + 5]); w.w = pk2(sp[p][8 * s + 6], sp[p][8 * s + 7]); pk[p][s] = __builtin_bit_cast(bf16x8, w); }
;     LAS const unsigned char* vb = VT + ((lane_ >> 4) & 1) * 32 + (lane_ & 3) * 8 + (4 * hi + ((lane_ & 15) >> 2)) * 64;
; #pragma unroll
;     for (int dh = 0; dh < 2; ++dh) {
;         bf16x8 vf[4];
; #pragma unroll
;         for (int ks = 0; ks < 4; ++ks) {
;             const s16x4 lo = __builtin_bit_cast(s16x4, __builtin_amdgcn_ds_read_tr16_b64_v4i16((LAS v4i16_t*)(vb + dh * 4096 + ks * 1024)));
;             const s16x4 hh = __builtin_bit_cast(s16x4, __builtin_amdgcn_ds_read_tr16_b64_v4i16((LAS v4i16_t*)(vb + dh * 4096 + ks * 1024 + 512)));
;             vf[ks] = (bf16x8){lo[0], lo[1], lo[2], lo[3], hh[0], hh[1], hh[2], hh[3]};
;         }
.Lat_drain:
	s_add_i32 s9, s77, 1
	s_and_b32 s9, s9, 3
	s_lshl_b32 s9, s9, 14
	v_add_u32_e32 v126, s9, v241
	ds_read_b64_tr_b16 v[192:193], v126 offset:8192
	ds_read_b64_tr_b16 v[194:195], v126 offset:8704
	ds_read_b64_tr_b16 v[208:209], v126 offset:12288
	ds_read_b64_tr_b16 v[210:211], v126 offset:12800
	ds_read_b64_tr_b16 v[196:197], v126 offset:9216
	ds_read_b64_tr_b16 v[198:199], v126 offset:9728
	ds_read_b64_tr_b16 v[212:213], v126 offset:13312
	ds_read_b64_tr_b16 v[214:215], v126 offset:13824
	ds_read_b64_tr_b16 v[200:201], v126 offset:10240
	ds_read_b64_tr_b16 v[202:203], v126 offset:10752
	ds_read_b64_tr_b16 v[216:217], v126 offset:14336
	ds_read_b64_tr_b16 v[218:219], v126 offset:14848
	ds_read_b64_tr_b16 v[204:205], v126 offset:11264
	ds_read_b64_tr_b16 v[206:207], v126 offset:11776
	ds_read_b64_tr_b16 v[220:221], v126 offset:15360
	ds_read_b64_tr_b16 v[222:223], v126 offset:15872
	v_pk_add_f32 v[118:119], v[50:51], v[52:53]
	v_cvt_pk_bf16_f32 v224, v50, v51
	v_pk_add_f32 v[122:123], v[54:55], v[56:57]
	v_cvt_pk_bf16_f32 v225, v52, v53
	v_pk_add_f32 v[124:125], v[34:35], v[36:37]
	v_cvt_pk_bf16_f32 v226, v54, v55
	v_pk_add_f32 v[118:119], v[118:119], v[58:59]
	v_cvt_pk_bf16_f32 v227, v56, v57
	v_pk_add_f32 v[122:123], v[122:123], v[60:61]
	v_cvt_pk_bf16_f32 v228, v58, v59
	v_pk_add_f32 v[124:125], v[124:125], v[38:39]
	v_cvt_pk_bf16_f32 v229, v60, v61
	v_pk_add_f32 v[118:119], v[118:119], v[62:63]
	v_cvt_pk_bf16_f32 v230, v62, v63
	v_pk_add_f32 v[122:123], v[122:123], v[64:65]
	v_cvt_pk_bf16_f32 v231, v64, v65
	v_pk_add_f32 v[124:125], v[124:125], v[40:41]
	v_cvt_pk_bf16_f32 v232, v34, v35
	v_pk_add_f32 v[118:119], v[118:119], v[42:43]
	v_cvt_pk_bf16_f32 v233, v36, v37
	v_pk_add_f32 v[122:123], v[122:123], v[44:45]
	v_cvt_pk_bf16_f32 v234, v38, v39
	v_pk_add_f32 v[124:125], v[124:125], v[46:47]
	v_cvt_pk_bf16_f32 v235, v40, v41
	v_pk_add_f32 v[118:119], v[118:119], v[48:49]
	v_cvt_pk_bf16_f32 v236, v42, v43
	v_pk_add_f32 v[118:119], v[118:119], v[122:123]
	v_cvt_pk_bf16_f32 v237, v44, v45
	v_pk_add_f32 v[118:119], v[118:119], v[124:125]
	v_cvt_pk_bf16_f32 v238, v46, v47
	v_add_f32_e32 v118, v118, v119
	v_cvt_pk_bf16_f32 v239, v48, v49
	s_cmp_eq_u32 s21, 1
	s_cbranch_scc1 .Lat_cep_38
	v_cndmask_b32_e64 v118, 0, v118, s[16:17]
	v_cndmask_b32_e64 v224, 0, v224, s[16:17]
	v_cndmask_b32_e64 v225, 0, v225, s[16:17]
	v_cndmask_b32_e64 v226, 0, v226, s[16:17]
	v_cndmask_b32_e64 v227, 0, v227, s[16:17]
	v_cndmask_b32_e64 v228, 0, v228, s[16:17]
	v_cndmask_b32_e64 v229, 0, v229, s[16:17]
	v_cndmask_b32_e64 v230, 0, v230, s[16:17]
	v_cndmask_b32_e64 v231, 0, v231, s[16:17]
	v_cndmask_b32_e64 v232, 0, v232, s[16:17]
	v_cndmask_b32_e64 v233, 0, v233, s[16:17]
	v_cndmask_b32_e64 v234, 0, v234, s[16:17]
	v_cndmask_b32_e64 v235, 0, v235, s[16:17]
	v_cndmask_b32_e64 v236, 0, v236, s[16:17]
	v_cndmask_b32_e64 v237, 0, v237, s[16:17]
	v_cndmask_b32_e64 v238, 0, v238, s[16:17]
	v_cndmask_b32_e64 v239, 0, v239, s[16:17]
